# conv stage 2: the gate (SGA) unpack and its wait moved from the stage start to the existing vmcnt(0) before first use, so the gate loads have the whole first reduction chain to land
# baseline (speedup 1.0000x reference)
.LBB0_555:
	v_lshrrev_b32_e32 v3, 12, v226
	v_cmp_gt_i32_e32 vcc, s10, v1
	v_lshrrev_b32_e32 v2, 4, v1
	v_add_u32_e32 v3, 32, v3
	v_cndmask_b32_e32 v2, v3, v2, vcc
	v_lshlrev_b32_e32 v2, 5, v2
	v_add3_u32 v2, v226, v2, s11
	v_ashrrev_i32_e32 v3, 31, v2
	v_lshlrev_b64 v[136:137], 10, v[2:3]
	v_lshl_add_u64 v[148:149], v[78:79], 0, v[136:137]
	s_nop 0
	s_nop 0
	global_load_dwordx2 v[134:135], v[18:19], off
	global_load_dwordx2 v[132:133], v[18:19], off offset:2048
	global_load_dwordx2 v[130:131], v[20:21], off
	global_load_dwordx2 v[128:129], v[22:23], off
	global_load_dwordx2 v[2:3], v[24:25], off
	global_load_dwordx2 v[4:5], v[26:27], off
	global_load_dwordx2 v[6:7], v[28:29], off
	global_load_dwordx2 v[8:9], v[30:31], off
	global_load_dwordx2 v[10:11], v[32:33], off
	global_load_dwordx2 v[12:13], v[34:35], off
	global_load_dwordx2 v[14:15], v[36:37], off
	global_load_dwordx2 v[16:17], v[38:39], off
	global_load_dwordx2 v[90:91], v[40:41], off
	global_load_dwordx2 v[92:93], v[42:43], off
	global_load_dwordx2 v[94:95], v[44:45], off
	global_load_dwordx2 v[96:97], v[46:47], off
	global_load_dwordx2 v[98:99], v[48:49], off
	global_load_dwordx2 v[100:101], v[50:51], off
	global_load_dwordx2 v[102:103], v[52:53], off
	global_load_dwordx2 v[104:105], v[54:55], off
	global_load_dwordx2 v[106:107], v[56:57], off
	global_load_dwordx2 v[108:109], v[58:59], off
	global_load_dwordx2 v[110:111], v[60:61], off
	global_load_dwordx2 v[112:113], v[62:63], off
	global_load_dwordx2 v[114:115], v[64:65], off
	global_load_dwordx2 v[116:117], v[66:67], off
	global_load_dwordx2 v[118:119], v[68:69], off
	global_load_dwordx2 v[120:121], v[70:71], off
	global_load_dwordx2 v[122:123], v[72:73], off
	global_load_dwordx2 v[124:125], v[74:75], off
	global_load_dwordx2 v[126:127], v[76:77], off
	global_load_dwordx2 v[136:137], v[80:81], off
	s_waitcnt lgkmcnt(0)
	s_barrier
	s_waitcnt vmcnt(32)
	v_mov_b32_e32 v138, v246
	v_mov_b32_e32 v139, v247
	v_mov_b32_e32 v140, v248
	v_mov_b32_e32 v141, v249
	v_mov_b32_e32 v142, v250
	v_mov_b32_e32 v143, v251
	v_add_u32_e32 v1, s8, v1
	s_nop 0
	v_lshlrev_b32_e32 v178, 16, v156
	s_nop 0
	v_lshlrev_b32_e32 v170, 16, v152
	s_nop 0
	v_and_b32_e32 v171, 0xffff0000, v152
	s_nop 0
	v_and_b32_e32 v179, 0xffff0000, v156
	s_nop 0
	v_lshlrev_b32_e32 v186, 16, v158
	v_and_b32_e32 v187, 0xffff0000, v158
	s_nop 0
	v_lshlrev_b32_e32 v162, 16, v150
	s_nop 0
	v_lshlrev_b32_e32 v154, 16, v145
	v_and_b32_e32 v155, 0xffff0000, v145
	v_and_b32_e32 v163, 0xffff0000, v150
	v_lshlrev_b32_e32 v196, 16, v160
	v_and_b32_e32 v197, 0xffff0000, v160
	v_lshlrev_b32_e32 v198, 16, v164
	v_and_b32_e32 v199, 0xffff0000, v164
	v_lshlrev_b32_e32 v150, 16, v151
	v_and_b32_e32 v151, 0xffff0000, v151
	v_lshlrev_b32_e32 v152, 16, v153
	v_and_b32_e32 v153, 0xffff0000, v153
	v_lshlrev_b32_e32 v156, 16, v157
	v_and_b32_e32 v157, 0xffff0000, v157
	v_lshlrev_b32_e32 v158, 16, v159
	v_and_b32_e32 v159, 0xffff0000, v159
	v_lshlrev_b32_e32 v160, 16, v161
	v_and_b32_e32 v161, 0xffff0000, v161
	v_lshlrev_b32_e32 v164, 16, v165
	v_and_b32_e32 v165, 0xffff0000, v165
	v_lshlrev_b32_e32 v180, 16, v181
	v_and_b32_e32 v181, 0xffff0000, v181
	v_lshlrev_b32_e32 v182, 16, v183
	v_and_b32_e32 v183, 0xffff0000, v183
	v_lshlrev_b32_e32 v184, 16, v185
	v_and_b32_e32 v185, 0xffff0000, v185
	v_lshlrev_b32_e32 v188, 16, v189
	v_and_b32_e32 v189, 0xffff0000, v189
	v_lshlrev_b32_e32 v190, 16, v191
	v_and_b32_e32 v191, 0xffff0000, v191
	v_lshlrev_b32_e32 v192, 16, v193
	v_and_b32_e32 v193, 0xffff0000, v193
	v_lshlrev_b32_e32 v194, 16, v195
	v_and_b32_e32 v195, 0xffff0000, v195
	v_lshlrev_b32_e32 v200, 16, v201
	v_and_b32_e32 v201, 0xffff0000, v201
	v_lshlrev_b32_e32 v202, 16, v203
	v_and_b32_e32 v203, 0xffff0000, v203
	v_lshlrev_b32_e32 v204, 16, v205
	v_and_b32_e32 v205, 0xffff0000, v205
	s_waitcnt vmcnt(0)
	v_lshlrev_b32_e32 v148, 16, v146
	v_and_b32_e32 v149, 0xffff0000, v146
	v_pk_fma_f32 v[148:149], v[148:149], v[134:135], v[136:137]
	v_lshlrev_b32_e32 v146, 16, v147
	v_pk_fma_f32 v[148:149], v[154:155], v[132:133], v[148:149]
	v_pk_fma_f32 v[154:155], v[154:155], v[134:135], v[136:137]
	v_pk_fma_f32 v[148:149], v[162:163], v[130:131], v[148:149]
	v_pk_fma_f32 v[154:155], v[162:163], v[132:133], v[154:155]
	v_pk_fma_f32 v[162:163], v[162:163], v[134:135], v[136:137]
	v_pk_fma_f32 v[148:149], v[170:171], v[128:129], v[148:149]
	v_pk_fma_f32 v[154:155], v[170:171], v[130:131], v[154:155]
	v_pk_fma_f32 v[162:163], v[170:171], v[132:133], v[162:163]
	v_pk_fma_f32 v[170:171], v[170:171], v[134:135], v[136:137]
	v_pk_fma_f32 v[148:149], v[178:179], v[2:3], v[148:149]
	v_pk_fma_f32 v[154:155], v[178:179], v[128:129], v[154:155]
	v_pk_fma_f32 v[162:163], v[178:179], v[130:131], v[162:163]
	v_pk_fma_f32 v[170:171], v[178:179], v[132:133], v[170:171]
	v_pk_fma_f32 v[178:179], v[178:179], v[134:135], v[136:137]
	v_pk_fma_f32 v[148:149], v[186:187], v[4:5], v[148:149]
	v_pk_fma_f32 v[154:155], v[186:187], v[2:3], v[154:155]
	v_pk_fma_f32 v[162:163], v[186:187], v[128:129], v[162:163]
	v_pk_fma_f32 v[170:171], v[186:187], v[130:131], v[170:171]
	v_pk_fma_f32 v[178:179], v[186:187], v[132:133], v[178:179]
	v_pk_fma_f32 v[186:187], v[186:187], v[134:135], v[136:137]
	v_pk_fma_f32 v[148:149], v[196:197], v[6:7], v[148:149]
	v_pk_fma_f32 v[154:155], v[196:197], v[4:5], v[154:155]
	v_pk_fma_f32 v[162:163], v[196:197], v[2:3], v[162:163]
	v_pk_fma_f32 v[170:171], v[196:197], v[128:129], v[170:171]
	v_pk_fma_f32 v[178:179], v[196:197], v[130:131], v[178:179]
	v_pk_fma_f32 v[186:187], v[196:197], v[132:133], v[186:187]
	v_pk_fma_f32 v[196:197], v[196:197], v[134:135], v[136:137]
	v_pk_fma_f32 v[148:149], v[198:199], v[8:9], v[148:149]
	v_pk_fma_f32 v[154:155], v[198:199], v[6:7], v[154:155]
	v_pk_fma_f32 v[162:163], v[198:199], v[4:5], v[162:163]
	v_pk_fma_f32 v[170:171], v[198:199], v[2:3], v[170:171]
	v_pk_fma_f32 v[178:179], v[198:199], v[128:129], v[178:179]
	v_pk_fma_f32 v[186:187], v[198:199], v[130:131], v[186:187]
	v_pk_fma_f32 v[228:229], v[198:199], v[132:133], v[196:197]
	v_pk_fma_f32 v[198:199], v[198:199], v[134:135], v[136:137]
	v_lshlrev_b32_e32 v196, 16, v166
	v_and_b32_e32 v197, 0xffff0000, v166
	v_pk_fma_f32 v[148:149], v[196:197], v[10:11], v[148:149]
	v_pk_fma_f32 v[154:155], v[196:197], v[8:9], v[154:155]
	v_pk_fma_f32 v[162:163], v[196:197], v[6:7], v[162:163]
	v_pk_fma_f32 v[170:171], v[196:197], v[4:5], v[170:171]
	v_pk_fma_f32 v[178:179], v[196:197], v[2:3], v[178:179]
	v_pk_fma_f32 v[186:187], v[196:197], v[128:129], v[186:187]
	v_pk_fma_f32 v[230:231], v[196:197], v[132:133], v[198:199]
	v_lshlrev_b32_e32 v198, 16, v168
	v_and_b32_e32 v199, 0xffff0000, v168
	v_pk_fma_f32 v[228:229], v[196:197], v[130:131], v[228:229]
	v_pk_fma_f32 v[148:149], v[198:199], v[12:13], v[148:149]
	v_pk_fma_f32 v[154:155], v[198:199], v[10:11], v[154:155]
	v_pk_fma_f32 v[162:163], v[198:199], v[8:9], v[162:163]
	v_pk_fma_f32 v[170:171], v[198:199], v[6:7], v[170:171]
	v_pk_fma_f32 v[178:179], v[198:199], v[4:5], v[178:179]
	v_pk_fma_f32 v[232:233], v[198:199], v[2:3], v[186:187]
	v_lshlrev_b32_e32 v186, 16, v172
	v_and_b32_e32 v187, 0xffff0000, v172
	v_pk_fma_f32 v[196:197], v[196:197], v[134:135], v[136:137]
	v_pk_fma_f32 v[228:229], v[198:199], v[128:129], v[228:229]
	v_pk_fma_f32 v[230:231], v[198:199], v[130:131], v[230:231]
	v_pk_fma_f32 v[148:149], v[186:187], v[14:15], v[148:149]
	v_pk_fma_f32 v[154:155], v[186:187], v[12:13], v[154:155]
	v_pk_fma_f32 v[162:163], v[186:187], v[10:11], v[162:163]
	v_pk_fma_f32 v[170:171], v[186:187], v[8:9], v[170:171]
	v_pk_fma_f32 v[234:235], v[186:187], v[6:7], v[178:179]
	v_lshlrev_b32_e32 v178, 16, v174
	v_and_b32_e32 v179, 0xffff0000, v174
	v_pk_fma_f32 v[196:197], v[198:199], v[132:133], v[196:197]
	v_pk_fma_f32 v[198:199], v[198:199], v[134:135], v[136:137]
	v_pk_fma_f32 v[232:233], v[186:187], v[4:5], v[232:233]
	v_pk_fma_f32 v[228:229], v[186:187], v[2:3], v[228:229]
	v_pk_fma_f32 v[230:231], v[186:187], v[128:129], v[230:231]
	v_pk_fma_f32 v[148:149], v[178:179], v[16:17], v[148:149]
	v_pk_fma_f32 v[154:155], v[178:179], v[14:15], v[154:155]
	v_pk_fma_f32 v[162:163], v[178:179], v[12:13], v[162:163]
	v_pk_fma_f32 v[236:237], v[178:179], v[10:11], v[170:171]
	v_lshlrev_b32_e32 v170, 16, v176
	v_and_b32_e32 v171, 0xffff0000, v176
	v_pk_fma_f32 v[196:197], v[186:187], v[130:131], v[196:197]
	v_pk_fma_f32 v[198:199], v[186:187], v[132:133], v[198:199]
	v_pk_fma_f32 v[186:187], v[186:187], v[134:135], v[136:137]
	v_pk_fma_f32 v[234:235], v[178:179], v[8:9], v[234:235]
	v_pk_fma_f32 v[232:233], v[178:179], v[6:7], v[232:233]
	v_pk_fma_f32 v[228:229], v[178:179], v[4:5], v[228:229]
	v_pk_fma_f32 v[230:231], v[178:179], v[2:3], v[230:231]
	v_pk_fma_f32 v[148:149], v[170:171], v[90:91], v[148:149]
	v_pk_fma_f32 v[154:155], v[170:171], v[16:17], v[154:155]
	v_pk_fma_f32 v[238:239], v[170:171], v[14:15], v[162:163]
	v_lshlrev_b32_e32 v162, 16, v144
	v_and_b32_e32 v163, 0xffff0000, v144
	v_pk_fma_f32 v[196:197], v[178:179], v[128:129], v[196:197]
	v_pk_fma_f32 v[198:199], v[178:179], v[130:131], v[198:199]
	v_pk_fma_f32 v[186:187], v[178:179], v[132:133], v[186:187]
	v_pk_fma_f32 v[178:179], v[178:179], v[134:135], v[136:137]
	v_pk_fma_f32 v[236:237], v[170:171], v[12:13], v[236:237]
	v_pk_fma_f32 v[234:235], v[170:171], v[10:11], v[234:235]
	v_pk_fma_f32 v[232:233], v[170:171], v[8:9], v[232:233]
	v_pk_fma_f32 v[228:229], v[170:171], v[6:7], v[228:229]
	v_pk_fma_f32 v[230:231], v[170:171], v[4:5], v[230:231]
	v_pk_fma_f32 v[144:145], v[162:163], v[92:93], v[148:149]
	v_pk_fma_f32 v[148:149], v[162:163], v[90:91], v[154:155]
	v_lshlrev_b32_e32 v154, 16, v143
	v_and_b32_e32 v155, 0xffff0000, v143
	v_pk_fma_f32 v[196:197], v[170:171], v[2:3], v[196:197]
	v_pk_fma_f32 v[198:199], v[170:171], v[128:129], v[198:199]
	v_pk_fma_f32 v[186:187], v[170:171], v[130:131], v[186:187]
	v_pk_fma_f32 v[178:179], v[170:171], v[132:133], v[178:179]
	v_pk_fma_f32 v[170:171], v[170:171], v[134:135], v[136:137]
	v_pk_fma_f32 v[238:239], v[162:163], v[16:17], v[238:239]
	v_pk_fma_f32 v[236:237], v[162:163], v[14:15], v[236:237]
	v_pk_fma_f32 v[234:235], v[162:163], v[12:13], v[234:235]
	v_pk_fma_f32 v[232:233], v[162:163], v[10:11], v[232:233]
	v_pk_fma_f32 v[228:229], v[162:163], v[8:9], v[228:229]
	v_pk_fma_f32 v[230:231], v[162:163], v[6:7], v[230:231]
	v_pk_fma_f32 v[144:145], v[154:155], v[94:95], v[144:145]
	v_pk_fma_f32 v[240:241], v[154:155], v[92:93], v[148:149]
	v_lshlrev_b32_e32 v148, 16, v142
	v_and_b32_e32 v149, 0xffff0000, v142
	v_pk_fma_f32 v[196:197], v[162:163], v[4:5], v[196:197]
	v_pk_fma_f32 v[198:199], v[162:163], v[2:3], v[198:199]
	v_pk_fma_f32 v[186:187], v[162:163], v[128:129], v[186:187]
	v_pk_fma_f32 v[178:179], v[162:163], v[130:131], v[178:179]
	v_pk_fma_f32 v[170:171], v[162:163], v[132:133], v[170:171]
	v_pk_fma_f32 v[162:163], v[162:163], v[134:135], v[136:137]
	v_pk_fma_f32 v[238:239], v[154:155], v[90:91], v[238:239]
	v_pk_fma_f32 v[236:237], v[154:155], v[16:17], v[236:237]
	v_pk_fma_f32 v[234:235], v[154:155], v[14:15], v[234:235]
	v_pk_fma_f32 v[232:233], v[154:155], v[12:13], v[232:233]
	v_pk_fma_f32 v[228:229], v[154:155], v[10:11], v[228:229]
	v_pk_fma_f32 v[230:231], v[154:155], v[8:9], v[230:231]
	v_pk_fma_f32 v[142:143], v[148:149], v[96:97], v[144:145]
	v_lshlrev_b32_e32 v144, 16, v141
	v_and_b32_e32 v145, 0xffff0000, v141
	v_pk_fma_f32 v[196:197], v[154:155], v[6:7], v[196:197]
	v_pk_fma_f32 v[198:199], v[154:155], v[4:5], v[198:199]
	v_pk_fma_f32 v[186:187], v[154:155], v[2:3], v[186:187]
	v_pk_fma_f32 v[178:179], v[154:155], v[128:129], v[178:179]
	v_pk_fma_f32 v[170:171], v[154:155], v[130:131], v[170:171]
	v_pk_fma_f32 v[162:163], v[154:155], v[132:133], v[162:163]
	v_pk_fma_f32 v[154:155], v[154:155], v[134:135], v[136:137]
	v_pk_fma_f32 v[134:135], v[148:149], v[134:135], v[136:137]
	v_pk_fma_f32 v[242:243], v[144:145], v[98:99], v[142:143]
	v_lshlrev_b32_e32 v142, 16, v140
	v_and_b32_e32 v143, 0xffff0000, v140
	v_pk_fma_f32 v[154:155], v[148:149], v[132:133], v[154:155]
	v_pk_fma_f32 v[132:133], v[144:145], v[132:133], v[134:135]
	v_lshlrev_b32_e32 v140, 16, v138
	v_and_b32_e32 v141, 0xffff0000, v138
	v_pk_fma_f32 v[162:163], v[148:149], v[130:131], v[162:163]
	v_pk_fma_f32 v[154:155], v[144:145], v[130:131], v[154:155]
	v_pk_fma_f32 v[130:131], v[142:143], v[130:131], v[132:133]
	v_lshlrev_b32_e32 v138, 16, v139
	v_and_b32_e32 v139, 0xffff0000, v139
	v_pk_fma_f32 v[170:171], v[148:149], v[128:129], v[170:171]
	v_pk_fma_f32 v[162:163], v[144:145], v[128:129], v[162:163]
	v_pk_fma_f32 v[154:155], v[142:143], v[128:129], v[154:155]
	v_pk_fma_f32 v[128:129], v[140:141], v[128:129], v[130:131]
	v_and_b32_e32 v147, 0xffff0000, v147
	v_pk_fma_f32 v[178:179], v[148:149], v[2:3], v[178:179]
	v_pk_fma_f32 v[170:171], v[144:145], v[2:3], v[170:171]
	v_pk_fma_f32 v[162:163], v[142:143], v[2:3], v[162:163]
	v_pk_fma_f32 v[154:155], v[140:141], v[2:3], v[154:155]
	v_pk_fma_f32 v[2:3], v[138:139], v[2:3], v[128:129]
	v_pk_fma_f32 v[198:199], v[148:149], v[6:7], v[198:199]
	v_pk_fma_f32 v[2:3], v[146:147], v[4:5], v[2:3]
	v_pk_fma_f32 v[186:187], v[148:149], v[4:5], v[186:187]
	v_pk_fma_f32 v[178:179], v[144:145], v[4:5], v[178:179]
	v_pk_fma_f32 v[170:171], v[142:143], v[4:5], v[170:171]
	v_pk_fma_f32 v[162:163], v[140:141], v[4:5], v[162:163]
	v_pk_fma_f32 v[154:155], v[138:139], v[4:5], v[154:155]
	v_pk_fma_f32 v[2:3], v[150:151], v[6:7], v[2:3]
	v_pk_fma_f32 v[228:229], v[148:149], v[12:13], v[228:229]
	v_pk_fma_f32 v[230:231], v[148:149], v[10:11], v[230:231]
	v_pk_fma_f32 v[196:197], v[148:149], v[8:9], v[196:197]
	v_pk_fma_f32 v[198:199], v[144:145], v[8:9], v[198:199]
	v_pk_fma_f32 v[186:187], v[144:145], v[6:7], v[186:187]
	v_pk_fma_f32 v[178:179], v[142:143], v[6:7], v[178:179]
	v_pk_fma_f32 v[170:171], v[140:141], v[6:7], v[170:171]
	v_pk_fma_f32 v[162:163], v[138:139], v[6:7], v[162:163]
	v_pk_fma_f32 v[154:155], v[146:147], v[6:7], v[154:155]
	v_pk_fma_f32 v[2:3], v[152:153], v[8:9], v[2:3]
	v_pk_fma_f32 v[228:229], v[144:145], v[14:15], v[228:229]
	v_pk_fma_f32 v[230:231], v[144:145], v[12:13], v[230:231]
	v_pk_fma_f32 v[196:197], v[144:145], v[10:11], v[196:197]
	v_pk_fma_f32 v[198:199], v[142:143], v[10:11], v[198:199]
	v_pk_fma_f32 v[186:187], v[142:143], v[8:9], v[186:187]
	v_pk_fma_f32 v[178:179], v[140:141], v[8:9], v[178:179]
	v_pk_fma_f32 v[170:171], v[138:139], v[8:9], v[170:171]
	v_pk_fma_f32 v[162:163], v[146:147], v[8:9], v[162:163]
	v_pk_fma_f32 v[154:155], v[150:151], v[8:9], v[154:155]
	v_pk_fma_f32 v[2:3], v[156:157], v[10:11], v[2:3]
	v_pk_fma_f32 v[232:233], v[148:149], v[14:15], v[232:233]
	v_pk_fma_f32 v[228:229], v[142:143], v[16:17], v[228:229]
	v_pk_fma_f32 v[230:231], v[142:143], v[14:15], v[230:231]
	v_pk_fma_f32 v[196:197], v[142:143], v[12:13], v[196:197]
	v_pk_fma_f32 v[198:199], v[140:141], v[12:13], v[198:199]
	v_pk_fma_f32 v[186:187], v[140:141], v[10:11], v[186:187]
	v_pk_fma_f32 v[178:179], v[138:139], v[10:11], v[178:179]
	v_pk_fma_f32 v[170:171], v[146:147], v[10:11], v[170:171]
	v_pk_fma_f32 v[162:163], v[150:151], v[10:11], v[162:163]
	v_pk_fma_f32 v[154:155], v[152:153], v[10:11], v[154:155]
	v_pk_fma_f32 v[2:3], v[158:159], v[12:13], v[2:3]
	v_pk_fma_f32 v[234:235], v[148:149], v[16:17], v[234:235]
	v_pk_fma_f32 v[232:233], v[144:145], v[16:17], v[232:233]
	v_pk_fma_f32 v[228:229], v[140:141], v[90:91], v[228:229]
	v_pk_fma_f32 v[230:231], v[140:141], v[16:17], v[230:231]
	v_pk_fma_f32 v[196:197], v[140:141], v[14:15], v[196:197]
	v_pk_fma_f32 v[198:199], v[138:139], v[14:15], v[198:199]
	v_pk_fma_f32 v[186:187], v[138:139], v[12:13], v[186:187]
	v_pk_fma_f32 v[178:179], v[146:147], v[12:13], v[178:179]
	v_pk_fma_f32 v[170:171], v[150:151], v[12:13], v[170:171]
	v_pk_fma_f32 v[162:163], v[152:153], v[12:13], v[162:163]
	v_pk_fma_f32 v[154:155], v[156:157], v[12:13], v[154:155]
	v_pk_fma_f32 v[2:3], v[160:161], v[14:15], v[2:3]
	v_pk_fma_f32 v[236:237], v[148:149], v[90:91], v[236:237]
	v_pk_fma_f32 v[234:235], v[144:145], v[90:91], v[234:235]
	v_pk_fma_f32 v[232:233], v[142:143], v[90:91], v[232:233]
	v_pk_fma_f32 v[228:229], v[138:139], v[92:93], v[228:229]
	v_pk_fma_f32 v[230:231], v[138:139], v[90:91], v[230:231]
	v_lshlrev_b32_e32 v166, 16, v167
	v_and_b32_e32 v167, 0xffff0000, v167
	v_pk_fma_f32 v[196:197], v[138:139], v[16:17], v[196:197]
	v_pk_fma_f32 v[198:199], v[146:147], v[16:17], v[198:199]
	v_pk_fma_f32 v[186:187], v[146:147], v[14:15], v[186:187]
	v_pk_fma_f32 v[178:179], v[150:151], v[14:15], v[178:179]
	v_pk_fma_f32 v[170:171], v[152:153], v[14:15], v[170:171]
	v_pk_fma_f32 v[162:163], v[156:157], v[14:15], v[162:163]
	v_pk_fma_f32 v[154:155], v[158:159], v[14:15], v[154:155]
	v_pk_fma_f32 v[2:3], v[164:165], v[16:17], v[2:3]
	v_pk_fma_f32 v[240:241], v[148:149], v[94:95], v[240:241]
	v_pk_fma_f32 v[238:239], v[148:149], v[92:93], v[238:239]
	v_pk_fma_f32 v[236:237], v[144:145], v[92:93], v[236:237]
	v_pk_fma_f32 v[234:235], v[142:143], v[92:93], v[234:235]
	v_pk_fma_f32 v[232:233], v[140:141], v[92:93], v[232:233]
	v_pk_fma_f32 v[228:229], v[146:147], v[94:95], v[228:229]
	v_pk_fma_f32 v[230:231], v[146:147], v[92:93], v[230:231]
	v_lshlrev_b32_e32 v168, 16, v169
	v_and_b32_e32 v169, 0xffff0000, v169
	v_pk_fma_f32 v[196:197], v[146:147], v[90:91], v[196:197]
	v_pk_fma_f32 v[198:199], v[150:151], v[90:91], v[198:199]
	v_pk_fma_f32 v[186:187], v[150:151], v[16:17], v[186:187]
	v_pk_fma_f32 v[178:179], v[152:153], v[16:17], v[178:179]
	v_pk_fma_f32 v[170:171], v[156:157], v[16:17], v[170:171]
	v_pk_fma_f32 v[162:163], v[158:159], v[16:17], v[162:163]
	v_pk_fma_f32 v[154:155], v[160:161], v[16:17], v[154:155]
	v_pk_fma_f32 v[2:3], v[166:167], v[90:91], v[2:3]
	v_pk_fma_f32 v[240:241], v[144:145], v[96:97], v[240:241]
	v_pk_fma_f32 v[238:239], v[144:145], v[94:95], v[238:239]
	v_pk_fma_f32 v[236:237], v[142:143], v[94:95], v[236:237]
	v_pk_fma_f32 v[234:235], v[140:141], v[94:95], v[234:235]
	v_pk_fma_f32 v[232:233], v[138:139], v[94:95], v[232:233]
	v_pk_fma_f32 v[228:229], v[150:151], v[96:97], v[228:229]
	v_pk_fma_f32 v[230:231], v[150:151], v[94:95], v[230:231]
	v_lshlrev_b32_e32 v172, 16, v173
	v_and_b32_e32 v173, 0xffff0000, v173
	v_pk_fma_f32 v[196:197], v[150:151], v[92:93], v[196:197]
	v_pk_fma_f32 v[198:199], v[152:153], v[92:93], v[198:199]
	v_pk_fma_f32 v[186:187], v[152:153], v[90:91], v[186:187]
	v_pk_fma_f32 v[178:179], v[156:157], v[90:91], v[178:179]
	v_pk_fma_f32 v[170:171], v[158:159], v[90:91], v[170:171]
	v_pk_fma_f32 v[162:163], v[160:161], v[90:91], v[162:163]
	v_pk_fma_f32 v[154:155], v[164:165], v[90:91], v[154:155]
	v_pk_fma_f32 v[2:3], v[168:169], v[92:93], v[2:3]
	v_pk_fma_f32 v[240:241], v[142:143], v[98:99], v[240:241]
	v_pk_fma_f32 v[238:239], v[142:143], v[96:97], v[238:239]
	v_pk_fma_f32 v[236:237], v[140:141], v[96:97], v[236:237]
	v_pk_fma_f32 v[234:235], v[138:139], v[96:97], v[234:235]
	v_pk_fma_f32 v[232:233], v[146:147], v[96:97], v[232:233]
	v_pk_fma_f32 v[228:229], v[152:153], v[98:99], v[228:229]
	v_pk_fma_f32 v[230:231], v[152:153], v[96:97], v[230:231]
	v_lshlrev_b32_e32 v174, 16, v175
	v_and_b32_e32 v175, 0xffff0000, v175
	v_pk_fma_f32 v[196:197], v[152:153], v[94:95], v[196:197]
	v_pk_fma_f32 v[198:199], v[156:157], v[94:95], v[198:199]
	v_pk_fma_f32 v[186:187], v[156:157], v[92:93], v[186:187]
	v_pk_fma_f32 v[178:179], v[158:159], v[92:93], v[178:179]
	v_pk_fma_f32 v[170:171], v[160:161], v[92:93], v[170:171]
	v_pk_fma_f32 v[162:163], v[164:165], v[92:93], v[162:163]
	v_pk_fma_f32 v[154:155], v[166:167], v[92:93], v[154:155]
	v_pk_fma_f32 v[2:3], v[172:173], v[94:95], v[2:3]
	v_pk_fma_f32 v[242:243], v[142:143], v[100:101], v[242:243]
	v_pk_fma_f32 v[240:241], v[140:141], v[100:101], v[240:241]
	v_pk_fma_f32 v[238:239], v[140:141], v[98:99], v[238:239]
	v_pk_fma_f32 v[236:237], v[138:139], v[98:99], v[236:237]
	v_pk_fma_f32 v[234:235], v[146:147], v[98:99], v[234:235]
	v_pk_fma_f32 v[232:233], v[150:151], v[98:99], v[232:233]
	v_pk_fma_f32 v[228:229], v[156:157], v[100:101], v[228:229]
	v_pk_fma_f32 v[230:231], v[156:157], v[98:99], v[230:231]
	v_lshlrev_b32_e32 v176, 16, v177
	v_and_b32_e32 v177, 0xffff0000, v177
	v_pk_fma_f32 v[196:197], v[156:157], v[96:97], v[196:197]
	v_pk_fma_f32 v[198:199], v[158:159], v[96:97], v[198:199]
	v_pk_fma_f32 v[186:187], v[158:159], v[94:95], v[186:187]
	v_pk_fma_f32 v[178:179], v[160:161], v[94:95], v[178:179]
	v_pk_fma_f32 v[170:171], v[164:165], v[94:95], v[170:171]
	v_pk_fma_f32 v[162:163], v[166:167], v[94:95], v[162:163]
	v_pk_fma_f32 v[154:155], v[168:169], v[94:95], v[154:155]
	v_pk_fma_f32 v[2:3], v[174:175], v[96:97], v[2:3]
	v_pk_fma_f32 v[242:243], v[140:141], v[102:103], v[242:243]
	v_pk_fma_f32 v[240:241], v[138:139], v[102:103], v[240:241]
	v_pk_fma_f32 v[238:239], v[138:139], v[100:101], v[238:239]
	v_pk_fma_f32 v[236:237], v[146:147], v[100:101], v[236:237]
	v_pk_fma_f32 v[234:235], v[150:151], v[100:101], v[234:235]
	v_pk_fma_f32 v[232:233], v[152:153], v[100:101], v[232:233]
	v_pk_fma_f32 v[228:229], v[158:159], v[102:103], v[228:229]
	v_pk_fma_f32 v[230:231], v[158:159], v[100:101], v[230:231]
	v_pk_fma_f32 v[196:197], v[158:159], v[98:99], v[196:197]
	v_pk_fma_f32 v[198:199], v[160:161], v[98:99], v[198:199]
	v_pk_fma_f32 v[186:187], v[160:161], v[96:97], v[186:187]
	v_pk_fma_f32 v[178:179], v[164:165], v[96:97], v[178:179]
	v_pk_fma_f32 v[170:171], v[166:167], v[96:97], v[170:171]
	v_pk_fma_f32 v[162:163], v[168:169], v[96:97], v[162:163]
	v_pk_fma_f32 v[154:155], v[172:173], v[96:97], v[154:155]
	v_pk_fma_f32 v[2:3], v[176:177], v[98:99], v[2:3]
	v_pk_fma_f32 v[242:243], v[138:139], v[104:105], v[242:243]
	v_pk_fma_f32 v[240:241], v[146:147], v[104:105], v[240:241]
	v_pk_fma_f32 v[238:239], v[146:147], v[102:103], v[238:239]
	v_pk_fma_f32 v[236:237], v[150:151], v[102:103], v[236:237]
	v_pk_fma_f32 v[234:235], v[152:153], v[102:103], v[234:235]
	v_pk_fma_f32 v[232:233], v[156:157], v[102:103], v[232:233]
	v_pk_fma_f32 v[228:229], v[160:161], v[104:105], v[228:229]
	v_pk_fma_f32 v[230:231], v[160:161], v[102:103], v[230:231]
	v_pk_fma_f32 v[196:197], v[160:161], v[100:101], v[196:197]
	v_pk_fma_f32 v[198:199], v[164:165], v[100:101], v[198:199]
	v_pk_fma_f32 v[186:187], v[164:165], v[98:99], v[186:187]
	v_pk_fma_f32 v[178:179], v[166:167], v[98:99], v[178:179]
	v_pk_fma_f32 v[170:171], v[168:169], v[98:99], v[170:171]
	v_pk_fma_f32 v[162:163], v[172:173], v[98:99], v[162:163]
	v_pk_fma_f32 v[154:155], v[174:175], v[98:99], v[154:155]
	v_pk_fma_f32 v[2:3], v[180:181], v[100:101], v[2:3]
	v_pk_fma_f32 v[242:243], v[146:147], v[106:107], v[242:243]
	v_pk_fma_f32 v[240:241], v[150:151], v[106:107], v[240:241]
	v_pk_fma_f32 v[238:239], v[150:151], v[104:105], v[238:239]
	v_pk_fma_f32 v[236:237], v[152:153], v[104:105], v[236:237]
	v_pk_fma_f32 v[234:235], v[156:157], v[104:105], v[234:235]
	v_pk_fma_f32 v[232:233], v[158:159], v[104:105], v[232:233]
	v_pk_fma_f32 v[228:229], v[164:165], v[106:107], v[228:229]
	v_pk_fma_f32 v[230:231], v[164:165], v[104:105], v[230:231]
	v_pk_fma_f32 v[196:197], v[164:165], v[102:103], v[196:197]
	v_pk_fma_f32 v[198:199], v[166:167], v[102:103], v[198:199]
	v_pk_fma_f32 v[186:187], v[166:167], v[100:101], v[186:187]
	v_pk_fma_f32 v[178:179], v[168:169], v[100:101], v[178:179]
	v_pk_fma_f32 v[170:171], v[172:173], v[100:101], v[170:171]
	v_pk_fma_f32 v[162:163], v[174:175], v[100:101], v[162:163]
	v_pk_fma_f32 v[154:155], v[176:177], v[100:101], v[154:155]
	v_pk_fma_f32 v[2:3], v[182:183], v[102:103], v[2:3]
	v_pk_fma_f32 v[242:243], v[150:151], v[108:109], v[242:243]
	v_pk_fma_f32 v[240:241], v[152:153], v[108:109], v[240:241]
	v_pk_fma_f32 v[238:239], v[152:153], v[106:107], v[238:239]
	v_pk_fma_f32 v[236:237], v[156:157], v[106:107], v[236:237]
	v_pk_fma_f32 v[234:235], v[158:159], v[106:107], v[234:235]
	v_pk_fma_f32 v[232:233], v[160:161], v[106:107], v[232:233]
	v_pk_fma_f32 v[228:229], v[166:167], v[108:109], v[228:229]
	v_add_u32_e32 v146, v215, v226
	v_add_u32_e32 v146, 0x2000, v146
	v_ashrrev_i32_e32 v147, 31, v146
	v_lshlrev_b64 v[144:145], 10, v[146:147]
	v_lshl_add_u64 v[144:145], v[86:87], 0, v[144:145]
	global_load_dwordx2 v[128:129], v[144:145], off
	global_load_dwordx2 v[130:131], v[144:145], off offset:512
	global_load_dwordx2 v[132:133], v[144:145], off offset:1024
	global_load_dwordx2 v[134:135], v[144:145], off offset:1536
	global_load_dwordx2 v[136:137], v[144:145], off offset:2048
	global_load_dwordx2 v[138:139], v[144:145], off offset:2560
	global_load_dwordx2 v[140:141], v[144:145], off offset:3072
	global_load_dwordx2 v[142:143], v[144:145], off offset:3584
	v_pk_fma_f32 v[230:231], v[166:167], v[106:107], v[230:231]
	v_pk_fma_f32 v[196:197], v[166:167], v[104:105], v[196:197]
	v_pk_fma_f32 v[198:199], v[168:169], v[104:105], v[198:199]
	v_pk_fma_f32 v[186:187], v[168:169], v[102:103], v[186:187]
	v_pk_fma_f32 v[178:179], v[172:173], v[102:103], v[178:179]
	v_pk_fma_f32 v[170:171], v[174:175], v[102:103], v[170:171]
	v_pk_fma_f32 v[162:163], v[176:177], v[102:103], v[162:163]
	v_pk_fma_f32 v[154:155], v[180:181], v[102:103], v[154:155]
	v_pk_fma_f32 v[2:3], v[184:185], v[104:105], v[2:3]
	v_pk_fma_f32 v[242:243], v[152:153], v[110:111], v[242:243]
	v_pk_fma_f32 v[240:241], v[156:157], v[110:111], v[240:241]
	v_pk_fma_f32 v[238:239], v[156:157], v[108:109], v[238:239]
	v_pk_fma_f32 v[236:237], v[158:159], v[108:109], v[236:237]
	v_pk_fma_f32 v[234:235], v[160:161], v[108:109], v[234:235]
	v_pk_fma_f32 v[232:233], v[164:165], v[108:109], v[232:233]
	v_pk_fma_f32 v[228:229], v[168:169], v[110:111], v[228:229]
	v_pk_fma_f32 v[230:231], v[168:169], v[108:109], v[230:231]
	v_pk_fma_f32 v[196:197], v[168:169], v[106:107], v[196:197]
	v_pk_fma_f32 v[198:199], v[172:173], v[106:107], v[198:199]
	v_pk_fma_f32 v[186:187], v[172:173], v[104:105], v[186:187]
	v_pk_fma_f32 v[178:179], v[174:175], v[104:105], v[178:179]
	v_pk_fma_f32 v[170:171], v[176:177], v[104:105], v[170:171]
	v_pk_fma_f32 v[162:163], v[180:181], v[104:105], v[162:163]
	v_pk_fma_f32 v[154:155], v[182:183], v[104:105], v[154:155]
	v_pk_fma_f32 v[2:3], v[188:189], v[106:107], v[2:3]
	v_pk_fma_f32 v[242:243], v[156:157], v[112:113], v[242:243]
	v_pk_fma_f32 v[240:241], v[158:159], v[112:113], v[240:241]
	v_pk_fma_f32 v[238:239], v[158:159], v[110:111], v[238:239]
	v_pk_fma_f32 v[236:237], v[160:161], v[110:111], v[236:237]
	v_pk_fma_f32 v[234:235], v[164:165], v[110:111], v[234:235]
	v_pk_fma_f32 v[232:233], v[166:167], v[110:111], v[232:233]
	v_pk_fma_f32 v[228:229], v[172:173], v[112:113], v[228:229]
	v_pk_fma_f32 v[230:231], v[172:173], v[110:111], v[230:231]
	v_pk_fma_f32 v[196:197], v[172:173], v[108:109], v[196:197]
	v_pk_fma_f32 v[198:199], v[174:175], v[108:109], v[198:199]
	v_pk_fma_f32 v[186:187], v[174:175], v[106:107], v[186:187]
	v_pk_fma_f32 v[178:179], v[176:177], v[106:107], v[178:179]
	v_pk_fma_f32 v[170:171], v[180:181], v[106:107], v[170:171]
	v_pk_fma_f32 v[162:163], v[182:183], v[106:107], v[162:163]
	v_pk_fma_f32 v[154:155], v[184:185], v[106:107], v[154:155]
	v_pk_fma_f32 v[2:3], v[190:191], v[108:109], v[2:3]
	v_pk_fma_f32 v[242:243], v[158:159], v[114:115], v[242:243]
	v_pk_fma_f32 v[240:241], v[160:161], v[114:115], v[240:241]
	v_pk_fma_f32 v[238:239], v[160:161], v[112:113], v[238:239]
	v_pk_fma_f32 v[236:237], v[164:165], v[112:113], v[236:237]
	v_pk_fma_f32 v[234:235], v[166:167], v[112:113], v[234:235]
	v_pk_fma_f32 v[232:233], v[168:169], v[112:113], v[232:233]
	v_pk_fma_f32 v[228:229], v[174:175], v[114:115], v[228:229]
	v_pk_fma_f32 v[230:231], v[174:175], v[112:113], v[230:231]
	v_pk_fma_f32 v[196:197], v[174:175], v[110:111], v[196:197]
	v_pk_fma_f32 v[198:199], v[176:177], v[110:111], v[198:199]
	v_pk_fma_f32 v[186:187], v[176:177], v[108:109], v[186:187]
	v_pk_fma_f32 v[178:179], v[180:181], v[108:109], v[178:179]
	v_pk_fma_f32 v[170:171], v[182:183], v[108:109], v[170:171]
	v_pk_fma_f32 v[162:163], v[184:185], v[108:109], v[162:163]
	v_pk_fma_f32 v[154:155], v[188:189], v[108:109], v[154:155]
	v_pk_fma_f32 v[2:3], v[192:193], v[110:111], v[2:3]
	v_pk_fma_f32 v[242:243], v[160:161], v[116:117], v[242:243]
	v_pk_fma_f32 v[240:241], v[164:165], v[116:117], v[240:241]
	v_pk_fma_f32 v[238:239], v[164:165], v[114:115], v[238:239]
	v_pk_fma_f32 v[236:237], v[166:167], v[114:115], v[236:237]
	v_pk_fma_f32 v[234:235], v[168:169], v[114:115], v[234:235]
	v_pk_fma_f32 v[232:233], v[172:173], v[114:115], v[232:233]
	v_pk_fma_f32 v[228:229], v[176:177], v[116:117], v[228:229]
	v_pk_fma_f32 v[230:231], v[176:177], v[114:115], v[230:231]
	v_pk_fma_f32 v[196:197], v[176:177], v[112:113], v[196:197]
	v_pk_fma_f32 v[198:199], v[180:181], v[112:113], v[198:199]
	v_pk_fma_f32 v[186:187], v[180:181], v[110:111], v[186:187]
	v_pk_fma_f32 v[178:179], v[182:183], v[110:111], v[178:179]
	v_pk_fma_f32 v[170:171], v[184:185], v[110:111], v[170:171]
	v_pk_fma_f32 v[162:163], v[188:189], v[110:111], v[162:163]
	v_pk_fma_f32 v[154:155], v[190:191], v[110:111], v[154:155]
	v_pk_fma_f32 v[2:3], v[194:195], v[112:113], v[2:3]
	v_pk_fma_f32 v[242:243], v[164:165], v[118:119], v[242:243]
	v_pk_fma_f32 v[240:241], v[166:167], v[118:119], v[240:241]
	v_pk_fma_f32 v[238:239], v[166:167], v[116:117], v[238:239]
	v_pk_fma_f32 v[236:237], v[168:169], v[116:117], v[236:237]
	v_pk_fma_f32 v[234:235], v[172:173], v[116:117], v[234:235]
	v_pk_fma_f32 v[232:233], v[174:175], v[116:117], v[232:233]
	v_pk_fma_f32 v[228:229], v[180:181], v[118:119], v[228:229]
	v_pk_fma_f32 v[230:231], v[180:181], v[116:117], v[230:231]
	v_pk_fma_f32 v[196:197], v[180:181], v[114:115], v[196:197]
	v_pk_fma_f32 v[198:199], v[182:183], v[114:115], v[198:199]
	v_pk_fma_f32 v[186:187], v[182:183], v[112:113], v[186:187]
	v_pk_fma_f32 v[178:179], v[184:185], v[112:113], v[178:179]
	v_pk_fma_f32 v[170:171], v[188:189], v[112:113], v[170:171]
	v_pk_fma_f32 v[162:163], v[190:191], v[112:113], v[162:163]
	v_pk_fma_f32 v[154:155], v[192:193], v[112:113], v[154:155]
	v_pk_fma_f32 v[2:3], v[200:201], v[114:115], v[2:3]
	v_pk_fma_f32 v[242:243], v[166:167], v[120:121], v[242:243]
	v_pk_fma_f32 v[240:241], v[168:169], v[120:121], v[240:241]
	v_pk_fma_f32 v[238:239], v[168:169], v[118:119], v[238:239]
	v_pk_fma_f32 v[236:237], v[172:173], v[118:119], v[236:237]
	v_pk_fma_f32 v[234:235], v[174:175], v[118:119], v[234:235]
	v_pk_fma_f32 v[232:233], v[176:177], v[118:119], v[232:233]
	v_pk_fma_f32 v[228:229], v[182:183], v[120:121], v[228:229]
	v_pk_fma_f32 v[230:231], v[182:183], v[118:119], v[230:231]
	v_pk_fma_f32 v[196:197], v[182:183], v[116:117], v[196:197]
	v_pk_fma_f32 v[198:199], v[184:185], v[116:117], v[198:199]
	v_pk_fma_f32 v[186:187], v[184:185], v[114:115], v[186:187]
	v_pk_fma_f32 v[178:179], v[188:189], v[114:115], v[178:179]
	v_pk_fma_f32 v[170:171], v[190:191], v[114:115], v[170:171]
	v_pk_fma_f32 v[162:163], v[192:193], v[114:115], v[162:163]
	v_pk_fma_f32 v[154:155], v[194:195], v[114:115], v[154:155]
	v_pk_fma_f32 v[2:3], v[202:203], v[116:117], v[2:3]
	v_pk_fma_f32 v[242:243], v[168:169], v[122:123], v[242:243]
	v_pk_fma_f32 v[240:241], v[172:173], v[122:123], v[240:241]
	v_pk_fma_f32 v[238:239], v[172:173], v[120:121], v[238:239]
	v_pk_fma_f32 v[236:237], v[174:175], v[120:121], v[236:237]
	v_pk_fma_f32 v[234:235], v[176:177], v[120:121], v[234:235]
	v_pk_fma_f32 v[232:233], v[180:181], v[120:121], v[232:233]
	v_pk_fma_f32 v[228:229], v[184:185], v[122:123], v[228:229]
	v_pk_fma_f32 v[230:231], v[184:185], v[120:121], v[230:231]
	v_pk_fma_f32 v[196:197], v[184:185], v[118:119], v[196:197]
	v_pk_fma_f32 v[198:199], v[188:189], v[118:119], v[198:199]
	v_pk_fma_f32 v[186:187], v[188:189], v[116:117], v[186:187]
	v_pk_fma_f32 v[178:179], v[190:191], v[116:117], v[178:179]
	v_lshlrev_b32_e32 v206, 16, v207
	v_and_b32_e32 v207, 0xffff0000, v207
	v_pk_fma_f32 v[170:171], v[192:193], v[116:117], v[170:171]
	v_pk_fma_f32 v[162:163], v[194:195], v[116:117], v[162:163]
	v_pk_fma_f32 v[154:155], v[200:201], v[116:117], v[154:155]
	v_pk_fma_f32 v[2:3], v[204:205], v[118:119], v[2:3]
	v_pk_fma_f32 v[242:243], v[172:173], v[124:125], v[242:243]
	v_pk_fma_f32 v[240:241], v[174:175], v[124:125], v[240:241]
	v_pk_fma_f32 v[238:239], v[174:175], v[122:123], v[238:239]
	v_pk_fma_f32 v[236:237], v[176:177], v[122:123], v[236:237]
	v_pk_fma_f32 v[234:235], v[180:181], v[122:123], v[234:235]
	v_pk_fma_f32 v[232:233], v[182:183], v[122:123], v[232:233]
	v_pk_fma_f32 v[228:229], v[188:189], v[124:125], v[228:229]
	v_pk_fma_f32 v[230:231], v[188:189], v[122:123], v[230:231]
	v_pk_fma_f32 v[196:197], v[188:189], v[120:121], v[196:197]
	v_pk_fma_f32 v[198:199], v[190:191], v[120:121], v[198:199]
	v_pk_fma_f32 v[186:187], v[190:191], v[118:119], v[186:187]
	v_pk_fma_f32 v[178:179], v[192:193], v[118:119], v[178:179]
	v_pk_fma_f32 v[170:171], v[194:195], v[118:119], v[170:171]
	v_lshlrev_b32_e32 v208, 16, v209
	v_and_b32_e32 v209, 0xffff0000, v209
	v_pk_fma_f32 v[162:163], v[200:201], v[118:119], v[162:163]
	v_pk_fma_f32 v[154:155], v[202:203], v[118:119], v[154:155]
	v_pk_fma_f32 v[2:3], v[206:207], v[120:121], v[2:3]
	v_pk_fma_f32 v[242:243], v[174:175], v[126:127], v[242:243]
	v_pk_fma_f32 v[240:241], v[176:177], v[126:127], v[240:241]
	v_pk_fma_f32 v[238:239], v[176:177], v[124:125], v[238:239]
	v_pk_fma_f32 v[236:237], v[180:181], v[124:125], v[236:237]
	v_pk_fma_f32 v[234:235], v[182:183], v[124:125], v[234:235]
	v_pk_fma_f32 v[232:233], v[184:185], v[124:125], v[232:233]
	v_pk_fma_f32 v[228:229], v[190:191], v[126:127], v[228:229]
	v_pk_fma_f32 v[230:231], v[190:191], v[124:125], v[230:231]
	v_pk_fma_f32 v[196:197], v[190:191], v[122:123], v[196:197]
	v_pk_fma_f32 v[198:199], v[192:193], v[122:123], v[198:199]
	v_pk_fma_f32 v[186:187], v[192:193], v[120:121], v[186:187]
	v_pk_fma_f32 v[178:179], v[194:195], v[120:121], v[178:179]
	v_pk_fma_f32 v[170:171], v[200:201], v[120:121], v[170:171]
	v_pk_fma_f32 v[162:163], v[202:203], v[120:121], v[162:163]
	v_lshlrev_b32_e32 v210, 16, v211
	v_and_b32_e32 v211, 0xffff0000, v211
	v_pk_fma_f32 v[154:155], v[204:205], v[120:121], v[154:155]
	v_pk_fma_f32 v[2:3], v[208:209], v[122:123], v[2:3]
	v_add_u32_e32 v120, v215, v226
	v_pk_fma_f32 v[238:239], v[180:181], v[126:127], v[238:239]
	v_pk_fma_f32 v[236:237], v[182:183], v[126:127], v[236:237]
	v_pk_fma_f32 v[234:235], v[184:185], v[126:127], v[234:235]
	v_pk_fma_f32 v[232:233], v[188:189], v[126:127], v[232:233]
	v_pk_fma_f32 v[230:231], v[192:193], v[126:127], v[230:231]
	ds_write2st64_b64 v214, v[242:243], v[240:241] offset1:4
	ds_write2st64_b64 v214, v[238:239], v[236:237] offset0:8 offset1:12
	ds_write2st64_b64 v214, v[234:235], v[232:233] offset0:16 offset1:20
	ds_write2st64_b64 v214, v[228:229], v[230:231] offset0:24 offset1:28
	v_pk_fma_f32 v[196:197], v[192:193], v[124:125], v[196:197]
	v_pk_fma_f32 v[198:199], v[194:195], v[124:125], v[198:199]
	v_pk_fma_f32 v[186:187], v[194:195], v[122:123], v[186:187]
	v_pk_fma_f32 v[178:179], v[200:201], v[122:123], v[178:179]
	v_pk_fma_f32 v[170:171], v[202:203], v[122:123], v[170:171]
	v_pk_fma_f32 v[162:163], v[204:205], v[122:123], v[162:163]
	v_pk_fma_f32 v[154:155], v[206:207], v[122:123], v[154:155]
	v_lshlrev_b32_e32 v228, 16, v227
	v_and_b32_e32 v229, 0xffff0000, v227
	v_pk_fma_f32 v[2:3], v[210:211], v[124:125], v[2:3]
	v_add_u32_e32 v98, 0x2000, v120
	v_pk_fma_f32 v[196:197], v[194:195], v[126:127], v[196:197]
	v_pk_fma_f32 v[198:199], v[200:201], v[126:127], v[198:199]
	v_pk_fma_f32 v[186:187], v[200:201], v[124:125], v[186:187]
	v_pk_fma_f32 v[178:179], v[202:203], v[124:125], v[178:179]
	v_pk_fma_f32 v[170:171], v[204:205], v[124:125], v[170:171]
	v_pk_fma_f32 v[162:163], v[206:207], v[124:125], v[162:163]
	v_pk_fma_f32 v[154:155], v[208:209], v[124:125], v[154:155]
	v_pk_fma_f32 v[2:3], v[228:229], v[126:127], v[2:3]
	v_ashrrev_i32_e32 v99, 31, v98
	v_pk_fma_f32 v[186:187], v[202:203], v[126:127], v[186:187]
	v_pk_fma_f32 v[178:179], v[204:205], v[126:127], v[178:179]
	v_pk_fma_f32 v[170:171], v[206:207], v[126:127], v[170:171]
	v_pk_fma_f32 v[162:163], v[208:209], v[126:127], v[162:163]
	v_pk_fma_f32 v[154:155], v[210:211], v[126:127], v[154:155]
	ds_write2st64_b64 v214, v[196:197], v[198:199] offset0:32 offset1:36
	ds_write2st64_b64 v214, v[186:187], v[178:179] offset0:40 offset1:44
	ds_write2st64_b64 v214, v[170:171], v[162:163] offset0:48 offset1:52
	ds_write2st64_b64 v214, v[154:155], v[2:3] offset0:56 offset1:60
	v_lshlrev_b64 v[2:3], 10, v[98:99]
	v_lshl_add_u64 v[2:3], v[86:87], 0, v[2:3]
	s_waitcnt lgkmcnt(0)
	s_barrier
	v_add_u32_e32 v226, s9, v226
	global_load_dwordx4 v[2:5], v[82:83], off offset:1024
	global_load_dwordx4 v[6:9], v[84:85], off offset:1024
	ds_read_b128 v[90:93], v216 offset:1024
	global_load_dwordx4 v[10:13], v[82:83], off
	global_load_dwordx4 v[14:17], v[84:85], off
	ds_read_b128 v[94:97], v216
	s_waitcnt lgkmcnt(1)
	v_pk_mul_f32 v[110:111], v[90:91], v[90:91]
	v_pk_mul_f32 v[108:109], v[92:93], v[92:93]
	s_waitcnt lgkmcnt(0)
	v_mov_b32_e32 v114, v94
	v_mov_b32_e32 v115, v96
	v_pk_mul_f32 v[114:115], v[114:115], v[114:115]
	v_pk_mul_f32 v[116:117], v[94:95], v[94:95]
	v_mov_b32_e32 v118, v114
	v_mov_b32_e32 v119, v94
	v_mov_b32_e32 v116, v117
	v_mov_b32_e32 v117, v95
	v_pk_mul_f32 v[112:113], v[96:97], v[96:97]
	v_pk_add_f32 v[116:117], v[118:119], v[116:117]
	v_pk_mov_b32 v[114:115], v[114:115], v[96:97] op_sel:[1,0]
	v_mov_b32_e32 v112, v113
	v_pk_add_f32 v[114:115], v[116:117], v[114:115]
	v_mov_b32_e32 v113, v97
	v_pk_add_f32 v[112:113], v[114:115], v[112:113]
	v_mov_b32_e32 v114, v110
	v_mov_b32_e32 v115, v90
	v_pk_add_f32 v[112:113], v[112:113], v[114:115]
	v_mov_b32_e32 v110, v111
	v_mov_b32_e32 v111, v91
	v_pk_add_f32 v[110:111], v[112:113], v[110:111]
	v_mov_b32_e32 v112, v108
	v_mov_b32_e32 v113, v92
	v_pk_add_f32 v[110:111], v[110:111], v[112:113]
	v_mov_b32_e32 v108, v109
	v_mov_b32_e32 v109, v93
	v_pk_add_f32 v[108:109], v[110:111], v[108:109]
	ds_bpermute_b32 v111, v217, v109
	ds_bpermute_b32 v110, v217, v108
	s_waitcnt lgkmcnt(0)
	v_pk_add_f32 v[108:109], v[108:109], v[110:111]
	ds_bpermute_b32 v111, v218, v109
	ds_bpermute_b32 v110, v218, v108
	s_waitcnt lgkmcnt(0)
	v_pk_add_f32 v[108:109], v[108:109], v[110:111]
	ds_bpermute_b32 v111, v219, v109
	ds_bpermute_b32 v110, v219, v108
	s_waitcnt lgkmcnt(0)
	v_pk_add_f32 v[108:109], v[108:109], v[110:111]
	ds_bpermute_b32 v111, v220, v109
	ds_bpermute_b32 v110, v220, v108
	s_waitcnt lgkmcnt(0)
	v_pk_add_f32 v[108:109], v[108:109], v[110:111]
	ds_bpermute_b32 v111, v221, v109
	ds_bpermute_b32 v110, v221, v108
	s_waitcnt lgkmcnt(0)
	v_pk_add_f32 v[108:109], v[108:109], v[110:111]
	ds_bpermute_b32 v111, v222, v109
	ds_bpermute_b32 v110, v222, v108
	s_waitcnt lgkmcnt(0)
	v_pk_add_f32 v[108:109], v[108:109], v[110:111]
	s_nop 0
	v_pk_mul_f32 v[108:109], v[108:109], s[6:7] op_sel_hi:[1,0]
	s_nop 0
	v_fma_f32 v110, -v109, v109, v108
	v_max_f32_e32 v110, 0, v110
	v_add_f32_e32 v110, 0x358637bd, v110
	v_cmp_gt_f32_e32 vcc, s22, v110
	v_mul_f32_e32 v111, 0x4b800000, v110
	v_pk_add_f32 v[94:95], v[94:95], v[108:109] op_sel:[0,1] neg_lo:[0,1] neg_hi:[0,1]
	v_cndmask_b32_e32 v110, v110, v111, vcc
	v_rsq_f32_e32 v110, v110
	v_pk_add_f32 v[96:97], v[96:97], v[108:109] op_sel:[0,1] neg_lo:[0,1] neg_hi:[0,1]
	v_pk_add_f32 v[90:91], v[90:91], v[108:109] op_sel:[0,1] neg_lo:[0,1] neg_hi:[0,1]
	v_pk_add_f32 v[92:93], v[92:93], v[108:109] op_sel:[0,1] neg_lo:[0,1] neg_hi:[0,1]
	v_mul_f32_e32 v111, 0x45800000, v110
	v_cndmask_b32_e32 v110, v110, v111, vcc
	v_pk_mul_f32 v[94:95], v[94:95], v[110:111] op_sel_hi:[1,0]
	s_waitcnt vmcnt(0)
	v_lshlrev_b32_e32 v100, 16, v128
	v_and_b32_e32 v101, 0xffff0000, v128
	v_lshlrev_b32_e32 v102, 16, v129
	v_and_b32_e32 v103, 0xffff0000, v129
	v_lshlrev_b32_e32 v104, 16, v130
	v_and_b32_e32 v105, 0xffff0000, v130
	v_lshlrev_b32_e32 v106, 16, v131
	v_and_b32_e32 v107, 0xffff0000, v131
	v_cmp_ge_i32_e64 s[98:99], s23, v1
	s_nop 0
	s_and_b64 s[98:99], s[98:99], exec
	s_cbranch_scc0 .Lcpf_skip_nxt
	v_lshrrev_b32_e32 v253, 12, v226
	v_cmp_gt_i32_e64 s[98:99], s10, v1
	v_lshrrev_b32_e32 v252, 4, v1
	v_add_u32_e32 v253, 32, v253
	v_cndmask_b32_e64 v252, v253, v252, s[98:99]
	v_lshlrev_b32_e32 v252, 5, v252
	v_add3_u32 v252, v226, v252, s11
	v_ashrrev_i32_e32 v253, 31, v252
	v_lshlrev_b64 v[252:253], 10, v[252:253]
	v_lshl_add_u64 v[252:253], v[78:79], 0, v[252:253]
	s_mov_b64 s[100:101], 0x1000
	v_lshl_add_u64 v[252:253], v[252:253], 0, s[100:101]
	s_mov_b64 s[100:101], 0x2000
	global_load_dword v146, v[252:253], off offset:-4096
	global_load_dword v145, v[252:253], off offset:-3072
	global_load_dword v150, v[252:253], off offset:-2048
	global_load_dword v152, v[252:253], off offset:-1024
	global_load_dword v156, v[252:253], off
	global_load_dword v158, v[252:253], off offset:1024
	global_load_dword v160, v[252:253], off offset:2048
	global_load_dword v164, v[252:253], off offset:3072
	v_lshl_add_u64 v[252:253], v[252:253], 0, s[100:101]
	global_load_dword v166, v[252:253], off offset:-4096
	global_load_dword v168, v[252:253], off offset:-3072
	global_load_dword v172, v[252:253], off offset:-2048
	global_load_dword v174, v[252:253], off offset:-1024
	global_load_dword v176, v[252:253], off
	global_load_dword v144, v[252:253], off offset:1024
	global_load_dword v251, v[252:253], off offset:2048
	global_load_dword v250, v[252:253], off offset:3072
	v_lshl_add_u64 v[252:253], v[252:253], 0, s[100:101]
	global_load_dword v249, v[252:253], off offset:-4096
	global_load_dword v248, v[252:253], off offset:-3072
	global_load_dword v246, v[252:253], off offset:-2048
	global_load_dword v247, v[252:253], off offset:-1024
	global_load_dword v147, v[252:253], off
	global_load_dword v151, v[252:253], off offset:1024
	global_load_dword v153, v[252:253], off offset:2048
	global_load_dword v157, v[252:253], off offset:3072
	v_lshl_add_u64 v[252:253], v[252:253], 0, s[100:101]
	global_load_dword v159, v[252:253], off offset:-4096
	global_load_dword v161, v[252:253], off offset:-3072
	global_load_dword v165, v[252:253], off offset:-2048
	global_load_dword v167, v[252:253], off offset:-1024
	global_load_dword v169, v[252:253], off
	global_load_dword v173, v[252:253], off offset:1024
	global_load_dword v175, v[252:253], off offset:2048
	global_load_dword v177, v[252:253], off offset:3072
	v_lshl_add_u64 v[252:253], v[252:253], 0, s[100:101]
	global_load_dword v181, v[252:253], off offset:-4096
	global_load_dword v183, v[252:253], off offset:-3072
	global_load_dword v185, v[252:253], off offset:-2048
	global_load_dword v189, v[252:253], off offset:-1024
	global_load_dword v191, v[252:253], off
	global_load_dword v193, v[252:253], off offset:1024
	global_load_dword v195, v[252:253], off offset:2048
	global_load_dword v201, v[252:253], off offset:3072
	v_lshl_add_u64 v[252:253], v[252:253], 0, s[100:101]
	global_load_dword v203, v[252:253], off offset:-4096
	global_load_dword v205, v[252:253], off offset:-3072
	global_load_dword v207, v[252:253], off offset:-2048
	global_load_dword v209, v[252:253], off offset:-1024
	global_load_dword v211, v[252:253], off
	global_load_dword v227, v[252:253], off offset:1024
